# A13: A11 + leaner RWKV helper block (exec-masked running products, packed k/e scaling, v/kr written for this half's rows only)
# speedup vs baseline: 1.0123x; 1.0090x over previous
.LBB0_185:
	s_and_b32 s17, s16, 1
	s_and_saveexec_b64 s[0:1], s[36:37]
	s_xor_b64 s[8:9], exec, s[0:1]
	s_cbranch_execz .LBB0_203
	s_lshl_b32 s98, s17, 3
	s_lshl_b32 s98, 0x00ff00ff, s98
	s_nop 3
	v_writelane_b32 v255, s98, 2
	s_ashr_i32 s2, s16, 5
	v_readlane_b32 s0, v251, 28
	s_ashr_i32 s3, s2, 31
	s_bfe_u32 s12, s16, 0x40001
	v_readlane_b32 s1, v251, 29
	s_lshl_b64 s[10:11], s[2:3], 11
	s_mov_b32 s15, s1
	s_lshl_b32 s14, s12, 7
	s_lshl_b32 s18, s12, 6
	v_lshl_add_u64 v[16:17], s[10:11], 0, v[104:105]
	v_lshl_add_u64 v[34:35], v[106:107], 0, s[14:15]
	s_movk_i32 s13, 0x1800
	v_lshl_add_u64 v[36:37], v[108:109], 0, s[14:15]
	v_or_b32_e32 v2, s18, v1
	v_readlane_b32 s40, v251, 9
	v_mad_u64_u32 v[14:15], s[0:1], v16, s13, v[34:35]
	v_mad_u64_u32 v[18:19], s[0:1], v16, s13, v[36:37]
	v_lshlrev_b32_e32 v12, 2, v2
	v_readlane_b32 s44, v251, 13
	v_readlane_b32 s45, v251, 14
	v_mad_i32_i24 v15, v17, s13, v15
	v_mad_i32_i24 v19, v17, s13, v19
	v_readlane_b32 s42, v251, 11
	v_readlane_b32 s43, v251, 12
	v_add_co_u32_e32 v10, vcc, s73, v14
	global_load_dwordx4 v[2:5], v12, s[44:45]
	global_load_dwordx2 v[20:21], v[14:15], off
	global_load_dwordx2 v[22:23], v[14:15], off offset:2048
	global_load_dwordx2 v[30:31], v[18:19], off
	global_load_dwordx4 v[6:9], v12, s[42:43]
	global_load_dwordx2 v[32:33], v[18:19], off offset:2048
	v_addc_co_u32_e32 v11, vcc, 0, v15, vcc
	v_readlane_b32 s46, v251, 15
	v_readlane_b32 s47, v251, 16
	global_load_dwordx2 v[24:25], v[10:11], off
	s_nop 3
	global_load_dwordx4 v[10:13], v12, s[46:47]
	s_waitcnt vmcnt(9)
	v_or_b32_e32 v26, s17, v1
	v_cmp_eq_u32_e64 s[0:1], 0, v26
	s_lshl_b32 s19, s12, 2
	v_readlane_b32 s12, v248, 15
	v_readlane_b32 s13, v248, 16
	s_add_u32 s12, s12, s19
	s_addc_u32 s13, s13, 0
	v_lshlrev_b64 v[16:17], 6, v[16:17]
	s_mov_b64 s[24:25], s[14:15]
	v_readlane_b32 s41, v251, 10
	v_readlane_b32 s48, v251, 17
	v_readlane_b32 s49, v251, 18
	v_readlane_b32 s50, v251, 19
	v_readlane_b32 s51, v251, 20
	v_readlane_b32 s52, v251, 21
	v_readlane_b32 s53, v251, 22
	v_readlane_b32 s54, v251, 23
	v_readlane_b32 s55, v251, 24
	s_waitcnt vmcnt(7)
	v_pk_add_f32 v[38:39], v[2:3], 1.0 op_sel_hi:[1,0] neg_lo:[1,0] neg_hi:[1,0]
	s_waitcnt vmcnt(5)
	v_lshlrev_b32_e32 v28, 16, v22
	v_and_b32_e32 v29, 0xffff0000, v22
	s_waitcnt vmcnt(2)
	v_lshlrev_b32_e32 v50, 16, v32
	v_and_b32_e32 v51, 0xffff0000, v32
	v_lshlrev_b32_e32 v26, 16, v20
	v_and_b32_e32 v27, 0xffff0000, v20
	v_lshlrev_b32_e32 v54, 16, v21
	v_and_b32_e32 v55, 0xffff0000, v21
	v_lshlrev_b32_e32 v43, 16, v30
	v_and_b32_e32 v45, 0xffff0000, v30
	v_pk_mul_f32 v[20:21], v[6:7], v[28:29]
	s_waitcnt vmcnt(1)
	v_and_b32_e32 v32, 0xffff0000, v25
	v_lshlrev_b32_e32 v30, 16, v25
	v_and_b32_e32 v44, 0xffff0000, v24
	v_lshlrev_b32_e32 v42, 16, v24
	v_pk_fma_f32 v[24:25], v[50:51], v[2:3], v[38:39]
	v_pk_add_f32 v[40:41], v[4:5], 1.0 op_sel_hi:[1,0] neg_lo:[1,0] neg_hi:[1,0]
	v_lshlrev_b32_e32 v56, 16, v33
	v_and_b32_e32 v57, 0xffff0000, v33
	v_pk_mul_f32 v[60:61], v[20:21], v[50:51]
	v_pk_mul_f32 v[50:51], v[24:25], v[28:29]
	v_lshlrev_b32_e32 v52, 16, v23
	v_and_b32_e32 v53, 0xffff0000, v23
	v_lshlrev_b32_e32 v48, 16, v31
	v_and_b32_e32 v31, 0xffff0000, v31
	v_pk_fma_f32 v[58:59], v[56:57], v[4:5], v[40:41]
	v_pk_mul_f32 v[24:25], v[50:51], v[26:27]
	v_pk_mul_f32 v[22:23], v[8:9], v[52:53]
	v_fma_f32 v33, v20, v20, 0
	v_exp_f32_e32 v49, v31
	v_pk_mul_f32 v[52:53], v[58:59], v[52:53]
	v_fma_f32 v31, v60, v26, 0
	v_fma_f32 v64, v50, v26, 0
	s_waitcnt vmcnt(0)
	v_fma_f32 v24, v24, v10, 0
	v_pk_mul_f32 v[56:57], v[22:23], v[56:57]
	v_fmac_f32_e32 v33, v21, v21
	v_pk_mul_f32 v[28:29], v[52:53], v[54:55]
	v_fmac_f32_e32 v31, v61, v27
	v_fmac_f32_e32 v64, v51, v27
	v_fmac_f32_e32 v24, v25, v11
	v_exp_f32_e32 v48, v48
	v_fmac_f32_e32 v33, v22, v22
	v_fmac_f32_e32 v31, v56, v54
	v_fmac_f32_e32 v64, v52, v54
	v_fmac_f32_e32 v24, v28, v12
	v_fmac_f32_e32 v33, v23, v23
	v_fmac_f32_e32 v31, v57, v55
	v_fmac_f32_e32 v64, v53, v55
	v_fmac_f32_e32 v24, v29, v13
	s_nop 1
	v_add_f32_dpp v33, v33, v33 quad_perm:[1,0,3,2] row_mask:0xf bank_mask:0xf
	v_add_f32_dpp v24, v24, v24 quad_perm:[1,0,3,2] row_mask:0xf bank_mask:0xf
	v_add_f32_dpp v31, v31, v31 quad_perm:[1,0,3,2] row_mask:0xf bank_mask:0xf
	v_add_f32_dpp v64, v64, v64 quad_perm:[1,0,3,2] row_mask:0xf bank_mask:0xf
	v_add_f32_dpp v33, v33, v33 quad_perm:[2,3,0,1] row_mask:0xf bank_mask:0xf
	v_add_f32_dpp v24, v24, v24 quad_perm:[2,3,0,1] row_mask:0xf bank_mask:0xf
	v_add_f32_dpp v31, v31, v31 quad_perm:[2,3,0,1] row_mask:0xf bank_mask:0xf
	v_add_f32_dpp v64, v64, v64 quad_perm:[2,3,0,1] row_mask:0xf bank_mask:0xf
	v_add_f32_dpp v33, v33, v33 row_half_mirror row_mask:0xf bank_mask:0xf
	v_add_f32_dpp v24, v24, v24 row_half_mirror row_mask:0xf bank_mask:0xf
	v_add_f32_dpp v31, v31, v31 row_half_mirror row_mask:0xf bank_mask:0xf
	v_add_f32_dpp v64, v64, v64 row_half_mirror row_mask:0xf bank_mask:0xf
	v_add_f32_dpp v33, v33, v33 row_mirror row_mask:0xf bank_mask:0xf
	v_add_f32_dpp v24, v24, v24 row_mirror row_mask:0xf bank_mask:0xf
	v_add_f32_dpp v31, v31, v31 row_mirror row_mask:0xf bank_mask:0xf
	v_add_f32_dpp v64, v64, v64 row_mirror row_mask:0xf bank_mask:0xf
	s_nop 0
	v_exp_f32_e32 v46, v43
	v_max_f32_e32 v25, v33, v33
	v_max_f32_e32 v25, 0x179abe15, v25
	v_exp_f32_e32 v47, v45
	v_pk_mul_f32 v[62:63], v[48:49], v[54:55]
	v_rsq_f32_e32 v54, v25
	ds_write_b128 v126, v[46:49] offset:24576
	s_mov_b32 exec_lo, 0xffff0000
	ds_read_b128 v[140:143], v126 offset:24320
	s_mov_b32 exec_lo, 0
	ds_read_b128 v[144:147], v126 offset:24064
	s_mov_b32 exec_hi, 0xffff0000
	ds_read_b128 v[148:151], v126 offset:23808
	s_mov_b64 exec, -1
	v_mov_b32_e32 v152, 1.0
	v_mov_b32_e32 v153, 1.0
	v_mov_b32_e32 v154, 1.0
	v_mov_b32_e32 v155, 1.0
	s_waitcnt lgkmcnt(0)
	s_mov_b32 exec_lo, 0xffff0000
	v_pk_mul_f32 v[152:153], v[152:153], v[140:141]
	v_pk_mul_f32 v[154:155], v[154:155], v[142:143]
	s_mov_b32 exec_lo, 0
	v_pk_mul_f32 v[152:153], v[152:153], v[144:145]
	v_pk_mul_f32 v[154:155], v[154:155], v[146:147]
	s_mov_b32 exec_hi, 0xffff0000
	v_pk_mul_f32 v[152:153], v[152:153], v[148:149]
	v_pk_mul_f32 v[154:155], v[154:155], v[150:151]
	s_mov_b64 exec, -1
	v_pk_mul_f32 v[156:157], v[152:153], v[46:47]
	v_pk_mul_f32 v[158:159], v[154:155], v[48:49]
	v_rcp_f32_e32 v160, v156
	v_rcp_f32_e32 v161, v157
	v_rcp_f32_e32 v162, v158
	v_rcp_f32_e32 v163, v159
	s_mov_b32 exec_lo, 0
	s_mov_b32 exec_hi, 0xffff0000
	v_mov_b32_e32 v160, 1.0
	v_mov_b32_e32 v161, 1.0
	v_mov_b32_e32 v162, 1.0
	v_mov_b32_e32 v163, 1.0
	ds_write_b128 v126, v[156:159] offset:24576
	s_mov_b64 exec, -1
	v_pk_mul_f32 v[164:165], v[50:51], v[160:161]
	v_pk_mul_f32 v[166:167], v[52:53], v[162:163]
	ds_write_b128 v126, v[164:167] offset:16384
	v_pk_mul_f32 v[58:59], v[46:47], v[26:27]
	v_mul_f32_e32 v43, v64, v42
	v_pk_mul_f32 v[20:21], v[20:21], v[54:55] op_sel_hi:[1,0]
	v_pk_mul_f32 v[22:23], v[22:23], v[54:55] op_sel_hi:[1,0]
	v_mul_f32_e64 v46, v31, -v54
	v_pk_mul_f32 v[28:29], v[56:57], v[54:55] op_sel_hi:[1,0]
	v_pk_mul_f32 v[26:27], v[60:61], v[54:55] op_sel_hi:[1,0]
	v_pk_fma_f32 v[48:49], v[46:47], v[22:23], v[62:63] op_sel_hi:[0,1,1]
	v_pk_fma_f32 v[46:47], v[46:47], v[20:21], v[58:59] op_sel_hi:[0,1,1]
	v_pk_mul_f32 v[168:169], v[26:27], v[160:161]
	v_pk_mul_f32 v[170:171], v[28:29], v[162:163]
	ds_write_b128 v126, v[168:171] offset:32768
	v_pk_mul_f32 v[172:173], v[20:21], v[152:153]
	v_pk_mul_f32 v[174:175], v[22:23], v[154:155]
	v_pk_mul_f32 v[176:177], v[46:47], v[152:153]
	v_pk_mul_f32 v[178:179], v[48:49], v[154:155]
	v_add_u32_e32 v201, 0x2000, v126
	ds_write2_b32 v126, v172, v176 offset1:1
	ds_write2_b32 v126, v173, v177 offset0:2 offset1:3
	ds_write2_b32 v201, v174, v178 offset1:1
	ds_write2_b32 v201, v175, v179 offset0:2 offset1:3
	v_mul_f32_e32 v45, v64, v44
	v_add_u32_e32 v20, v124, v127
	v_mul_f32_e32 v31, v64, v30
	v_mul_f32_e32 v33, v64, v32
	v_lshl_add_u64 v[22:23], s[12:13], 0, v[16:17]
	v_readlane_b32 s98, v255, 2
	s_nop 3
	s_mov_b32 exec_lo, s98
	s_mov_b32 exec_hi, s98
	ds_write_b128 v20, v[42:45] offset:40960
	ds_write_b128 v20, v[30:33] offset:40976
	s_mov_b64 exec, -1
	s_and_saveexec_b64 s[14:15], s[0:1]
	s_cbranch_execz .LBB0_188
	global_store_dword v[22:23], v24, off
.LBB0_188:
	s_or_b64 exec, exec, s[14:15]
	v_add_co_u32_e32 v24, vcc, 0x18000, v14
	s_mov_b64 s[14:15], 0x18000
	s_nop 0
	v_addc_co_u32_e32 v25, vcc, 0, v15, vcc
	v_lshl_add_u64 v[16:17], v[14:15], 0, s[14:15]
	v_add_co_u32_e32 v14, vcc, 0x19000, v14
	global_load_dwordx2 v[24:25], v[24:25], off
	s_nop 0
	global_load_dwordx2 v[32:33], v[16:17], off offset:2048
	v_addc_co_u32_e32 v15, vcc, 0, v15, vcc
	global_load_dwordx2 v[54:55], v[14:15], off
	v_add_co_u32_e32 v14, vcc, 0x18000, v18
	v_lshl_add_u64 v[20:21], v[18:19], 0, s[14:15]
	s_nop 0
	v_addc_co_u32_e32 v15, vcc, 0, v19, vcc
	global_load_dwordx2 v[14:15], v[14:15], off
	s_nop 0
	global_load_dwordx2 v[18:19], v[20:21], off offset:2048
	s_waitcnt vmcnt(4)
	v_lshlrev_b32_e32 v50, 16, v25
	s_waitcnt vmcnt(3)
	v_and_b32_e32 v17, 0xffff0000, v32
	v_and_b32_e32 v51, 0xffff0000, v25
	s_waitcnt vmcnt(1)
	v_lshlrev_b32_e32 v16, 16, v14
	s_waitcnt vmcnt(0)
	v_lshlrev_b32_e32 v42, 16, v18
	v_and_b32_e32 v43, 0xffff0000, v18
	v_and_b32_e32 v14, 0xffff0000, v14
	v_exp_f32_e32 v26, v16
	v_lshlrev_b32_e32 v16, 16, v32
	v_pk_fma_f32 v[28:29], v[42:43], v[2:3], v[38:39]
	v_lshlrev_b32_e32 v44, 16, v15
	v_and_b32_e32 v45, 0xffff0000, v15
	v_exp_f32_e32 v27, v14
	v_lshlrev_b32_e32 v14, 16, v24
	v_and_b32_e32 v15, 0xffff0000, v24
	v_pk_mul_f32 v[30:31], v[28:29], v[16:17]
	v_lshlrev_b32_e32 v18, 16, v19
	v_pk_mul_f32 v[28:29], v[30:31], v[14:15]
	v_and_b32_e32 v19, 0xffff0000, v19
	v_fma_f32 v24, v28, v10, 0
	v_lshlrev_b32_e32 v32, 16, v33
	v_and_b32_e32 v33, 0xffff0000, v33
	v_pk_fma_f32 v[46:47], v[18:19], v[4:5], v[40:41]
	v_fmac_f32_e32 v24, v29, v11
	v_exp_f32_e32 v28, v44
	v_exp_f32_e32 v29, v45
	v_pk_mul_f32 v[44:45], v[8:9], v[32:33]
	v_pk_mul_f32 v[32:33], v[46:47], v[32:33]
	v_pk_mul_f32 v[20:21], v[6:7], v[16:17]
	v_pk_mul_f32 v[46:47], v[32:33], v[50:51]
	v_fma_f32 v48, v20, v20, 0
	v_fmac_f32_e32 v24, v46, v12
	v_fmac_f32_e32 v24, v47, v13
	v_pk_mul_f32 v[46:47], v[20:21], v[42:43]
	v_fma_f32 v17, v30, v14, 0
	v_fma_f32 v25, v46, v14, 0
	v_fmac_f32_e32 v48, v21, v21
	v_fmac_f32_e32 v17, v31, v15
	v_fmac_f32_e32 v25, v47, v15
	v_pk_mul_f32 v[18:19], v[44:45], v[18:19]
	v_fmac_f32_e32 v48, v44, v44
	v_fmac_f32_e32 v17, v32, v50
	v_fmac_f32_e32 v25, v18, v50
	v_fmac_f32_e32 v48, v45, v45
	v_fmac_f32_e32 v17, v33, v51
	v_fmac_f32_e32 v25, v19, v51
	s_nop 1
	v_add_f32_dpp v48, v48, v48 quad_perm:[1,0,3,2] row_mask:0xf bank_mask:0xf
	v_add_f32_dpp v24, v24, v24 quad_perm:[1,0,3,2] row_mask:0xf bank_mask:0xf
	v_add_f32_dpp v25, v25, v25 quad_perm:[1,0,3,2] row_mask:0xf bank_mask:0xf
	v_add_f32_dpp v17, v17, v17 quad_perm:[1,0,3,2] row_mask:0xf bank_mask:0xf
	v_add_f32_dpp v48, v48, v48 quad_perm:[2,3,0,1] row_mask:0xf bank_mask:0xf
	v_add_f32_dpp v24, v24, v24 quad_perm:[2,3,0,1] row_mask:0xf bank_mask:0xf
	v_add_f32_dpp v25, v25, v25 quad_perm:[2,3,0,1] row_mask:0xf bank_mask:0xf
	v_add_f32_dpp v17, v17, v17 quad_perm:[2,3,0,1] row_mask:0xf bank_mask:0xf
	v_add_f32_dpp v48, v48, v48 row_half_mirror row_mask:0xf bank_mask:0xf
	v_add_f32_dpp v24, v24, v24 row_half_mirror row_mask:0xf bank_mask:0xf
	v_add_f32_dpp v25, v25, v25 row_half_mirror row_mask:0xf bank_mask:0xf
	v_add_f32_dpp v17, v17, v17 row_half_mirror row_mask:0xf bank_mask:0xf
	v_add_f32_dpp v48, v48, v48 row_mirror row_mask:0xf bank_mask:0xf
	v_add_f32_dpp v24, v24, v24 row_mirror row_mask:0xf bank_mask:0xf
	v_add_f32_dpp v25, v25, v25 row_mirror row_mask:0xf bank_mask:0xf
	v_add_f32_dpp v17, v17, v17 row_mirror row_mask:0xf bank_mask:0xf
	s_nop 0
	v_pk_mul_f32 v[14:15], v[26:27], v[14:15]
	v_max_f32_e32 v16, v48, v48
	v_max_f32_e32 v16, 0x179abe15, v16
	v_rsq_f32_e32 v16, v16
	s_nop 0
	v_pk_mul_f32 v[42:43], v[20:21], v[16:17] op_sel_hi:[1,0]
	v_pk_mul_f32 v[44:45], v[44:45], v[16:17] op_sel_hi:[1,0]
	v_pk_mul_f32 v[48:49], v[18:19], v[16:17] op_sel_hi:[1,0]
	v_pk_mul_f32 v[46:47], v[46:47], v[16:17] op_sel_hi:[1,0]
	v_pk_mul_f32 v[18:19], v[28:29], v[50:51]
	v_mul_f32_e64 v16, v25, -v16
	v_pk_fma_f32 v[52:53], v[16:17], v[44:45], v[18:19] op_sel_hi:[0,1,1]
	v_pk_fma_f32 v[50:51], v[16:17], v[42:43], v[14:15] op_sel_hi:[0,1,1]
	v_and_b32_e32 v16, 0xffff0000, v55
	v_lshlrev_b32_e32 v14, 16, v55
	v_and_b32_e32 v20, 0xffff0000, v54
	v_lshlrev_b32_e32 v18, 16, v54
	v_mul_f32_e32 v19, v17, v18
	v_mul_f32_e32 v21, v17, v20
	v_add_u32_e32 v25, v124, v130
	v_mul_f32_e32 v15, v17, v14
	v_mul_f32_e32 v17, v17, v16
	ds_write_b128 v129, v[26:29] offset:24576
	s_mov_b32 exec_lo, 0xffff0000
	ds_read_b128 v[140:143], v129 offset:24320
	s_mov_b32 exec_lo, 0
	ds_read_b128 v[144:147], v129 offset:24064
	s_mov_b32 exec_hi, 0xffff0000
	ds_read_b128 v[148:151], v129 offset:23808
	s_mov_b64 exec, -1
	v_mov_b32_e32 v152, 1.0
	v_mov_b32_e32 v153, 1.0
	v_mov_b32_e32 v154, 1.0
	v_mov_b32_e32 v155, 1.0
	s_waitcnt lgkmcnt(0)
	s_mov_b32 exec_lo, 0xffff0000
	v_pk_mul_f32 v[152:153], v[152:153], v[140:141]
	v_pk_mul_f32 v[154:155], v[154:155], v[142:143]
	s_mov_b32 exec_lo, 0
	v_pk_mul_f32 v[152:153], v[152:153], v[144:145]
	v_pk_mul_f32 v[154:155], v[154:155], v[146:147]
	s_mov_b32 exec_hi, 0xffff0000
	v_pk_mul_f32 v[152:153], v[152:153], v[148:149]
	v_pk_mul_f32 v[154:155], v[154:155], v[150:151]
	s_mov_b64 exec, -1
	v_pk_mul_f32 v[156:157], v[152:153], v[26:27]
	v_pk_mul_f32 v[158:159], v[154:155], v[28:29]
	v_rcp_f32_e32 v160, v156
	v_rcp_f32_e32 v161, v157
	v_rcp_f32_e32 v162, v158
	v_rcp_f32_e32 v163, v159
	s_mov_b32 exec_lo, 0
	s_mov_b32 exec_hi, 0xffff0000
	v_mov_b32_e32 v160, 1.0
	v_mov_b32_e32 v161, 1.0
	v_mov_b32_e32 v162, 1.0
	v_mov_b32_e32 v163, 1.0
	ds_write_b128 v129, v[156:159] offset:24576
	s_mov_b64 exec, -1
	v_pk_mul_f32 v[164:165], v[30:31], v[160:161]
	v_pk_mul_f32 v[166:167], v[32:33], v[162:163]
	ds_write_b128 v129, v[164:167] offset:16384
	v_pk_mul_f32 v[168:169], v[46:47], v[160:161]
	v_pk_mul_f32 v[170:171], v[48:49], v[162:163]
	ds_write_b128 v129, v[168:171] offset:32768
	v_pk_mul_f32 v[172:173], v[42:43], v[152:153]
	v_pk_mul_f32 v[174:175], v[44:45], v[154:155]
	v_pk_mul_f32 v[176:177], v[50:51], v[152:153]
	v_pk_mul_f32 v[178:179], v[52:53], v[154:155]
	v_add_u32_e32 v201, 0x2000, v129
	ds_write2_b32 v129, v172, v176 offset1:1
	ds_write2_b32 v129, v173, v177 offset0:2 offset1:3
	ds_write2_b32 v201, v174, v178 offset1:1
	ds_write2_b32 v201, v175, v179 offset0:2 offset1:3
	v_readlane_b32 s98, v255, 2
	s_nop 3
	s_mov_b32 exec_lo, s98
	s_mov_b32 exec_hi, s98
	ds_write_b128 v25, v[18:21] offset:40960
	ds_write_b128 v25, v[14:17] offset:40976
	s_mov_b64 exec, -1
	s_and_saveexec_b64 s[14:15], s[0:1]
	s_cbranch_execz .LBB0_190
	global_store_dword v[22:23], v24, off offset:1024
.LBB0_190:
	s_or_b64 exec, exec, s[14:15]
	v_lshl_add_u64 v[42:43], v[104:105], 0, s[10:11]
	v_lshl_add_u64 v[46:47], v[42:43], 0, 32
	s_movk_i32 s20, 0x1800
	v_mad_u64_u32 v[14:15], s[14:15], v46, s20, v[34:35]
	v_mad_i32_i24 v15, v47, s20, v15
	v_add_co_u32_e32 v18, vcc, s73, v14
	v_mad_u64_u32 v[16:17], s[14:15], v46, s20, v[36:37]
	s_nop 0
	v_addc_co_u32_e32 v19, vcc, 0, v15, vcc
	v_mad_i32_i24 v17, v47, s20, v17
	global_load_dwordx2 v[20:21], v[14:15], off
	global_load_dwordx2 v[22:23], v[14:15], off offset:2048
	global_load_dwordx2 v[54:55], v[18:19], off
	s_nop 0
	global_load_dwordx2 v[18:19], v[16:17], off
	global_load_dwordx2 v[24:25], v[16:17], off offset:2048
	s_mov_b64 s[14:15], 0x18000
	v_lshl_add_u64 v[26:27], v[14:15], 0, s[14:15]
	v_lshl_add_u64 v[28:29], v[16:17], 0, s[14:15]
	s_mov_b32 s14, 0x19000
	v_add_co_u32_e32 v14, vcc, s14, v14
	s_mov_b32 s14, 0x18000
	s_nop 0
	v_addc_co_u32_e32 v15, vcc, 0, v15, vcc
	global_load_dwordx2 v[50:51], v[14:15], off offset:-4096
	global_load_dwordx2 v[48:49], v[26:27], off offset:2048
	global_load_dwordx2 v[44:45], v[14:15], off
	v_add_co_u32_e32 v14, vcc, s14, v16
	s_waitcnt vmcnt(7)
	v_lshlrev_b32_e32 v60, 16, v20
	v_addc_co_u32_e32 v15, vcc, 0, v17, vcc
	global_load_dwordx2 v[56:57], v[14:15], off
	global_load_dwordx2 v[52:53], v[28:29], off offset:2048
	s_waitcnt vmcnt(5)
	v_lshlrev_b32_e32 v28, 16, v24
	v_and_b32_e32 v29, 0xffff0000, v24
	v_lshlrev_b32_e32 v14, 16, v18
	v_and_b32_e32 v15, 0xffff0000, v18
	v_lshlrev_b32_e32 v30, 16, v19
	v_and_b32_e32 v31, 0xffff0000, v19
	v_lshlrev_b32_e32 v16, 16, v22
	v_and_b32_e32 v17, 0xffff0000, v22
	v_pk_fma_f32 v[18:19], v[28:29], v[2:3], v[38:39]
	v_and_b32_e32 v61, 0xffff0000, v20
	v_pk_mul_f32 v[18:19], v[18:19], v[16:17]
	v_pk_mul_f32 v[26:27], v[6:7], v[16:17]
	v_pk_mul_f32 v[16:17], v[18:19], v[60:61]
	v_lshlrev_b32_e32 v24, 16, v25
	v_fma_f32 v58, v16, v10, 0
	v_and_b32_e32 v25, 0xffff0000, v25
	v_fmac_f32_e32 v58, v17, v11
	v_exp_f32_e32 v16, v30
	v_exp_f32_e32 v17, v31
	v_lshlrev_b32_e32 v62, 16, v21
	v_and_b32_e32 v63, 0xffff0000, v21
	v_lshlrev_b32_e32 v20, 16, v23
	v_and_b32_e32 v21, 0xffff0000, v23
	v_pk_fma_f32 v[30:31], v[24:25], v[4:5], v[40:41]
	v_pk_mul_f32 v[64:65], v[26:27], v[28:29]
	v_fma_f32 v32, v26, v26, 0
	v_fma_f32 v59, v18, v60, 0
	v_pk_mul_f32 v[22:23], v[8:9], v[20:21]
	v_pk_mul_f32 v[20:21], v[30:31], v[20:21]
	v_fma_f32 v67, v64, v60, 0
	v_fmac_f32_e32 v32, v27, v27
	v_fmac_f32_e32 v59, v19, v61
	v_pk_mul_f32 v[30:31], v[20:21], v[62:63]
	v_fmac_f32_e32 v67, v65, v61
	v_pk_mul_f32 v[24:25], v[22:23], v[24:25]
	v_fmac_f32_e32 v32, v22, v22
	v_fmac_f32_e32 v58, v30, v12
	v_fmac_f32_e32 v59, v20, v62
	v_fmac_f32_e32 v67, v24, v62
	v_fmac_f32_e32 v32, v23, v23
	v_fmac_f32_e32 v58, v31, v13
	v_fmac_f32_e32 v59, v21, v63
	v_fmac_f32_e32 v67, v25, v63
	s_waitcnt lgkmcnt(0)
	s_barrier
	s_nop 1
	v_add_f32_dpp v32, v32, v32 quad_perm:[1,0,3,2] row_mask:0xf bank_mask:0xf
	v_add_f32_dpp v58, v58, v58 quad_perm:[1,0,3,2] row_mask:0xf bank_mask:0xf
	v_add_f32_dpp v67, v67, v67 quad_perm:[1,0,3,2] row_mask:0xf bank_mask:0xf
	v_add_f32_dpp v59, v59, v59 quad_perm:[1,0,3,2] row_mask:0xf bank_mask:0xf
	v_add_f32_dpp v32, v32, v32 quad_perm:[2,3,0,1] row_mask:0xf bank_mask:0xf
	v_add_f32_dpp v58, v58, v58 quad_perm:[2,3,0,1] row_mask:0xf bank_mask:0xf
	v_add_f32_dpp v67, v67, v67 quad_perm:[2,3,0,1] row_mask:0xf bank_mask:0xf
	v_add_f32_dpp v59, v59, v59 quad_perm:[2,3,0,1] row_mask:0xf bank_mask:0xf
	v_add_f32_dpp v32, v32, v32 row_half_mirror row_mask:0xf bank_mask:0xf
	v_add_f32_dpp v58, v58, v58 row_half_mirror row_mask:0xf bank_mask:0xf
	v_add_f32_dpp v67, v67, v67 row_half_mirror row_mask:0xf bank_mask:0xf
	v_add_f32_dpp v59, v59, v59 row_half_mirror row_mask:0xf bank_mask:0xf
	v_add_f32_dpp v32, v32, v32 row_mirror row_mask:0xf bank_mask:0xf
	v_add_f32_dpp v58, v58, v58 row_mirror row_mask:0xf bank_mask:0xf
	v_add_f32_dpp v67, v67, v67 row_mirror row_mask:0xf bank_mask:0xf
	v_add_f32_dpp v59, v59, v59 row_mirror row_mask:0xf bank_mask:0xf
	s_nop 0
	v_exp_f32_e32 v14, v14
	v_max_f32_e32 v28, v32, v32
	v_max_f32_e32 v28, 0x179abe15, v28
	v_exp_f32_e32 v15, v15
	v_rsq_f32_e32 v66, v28
	s_nop 0
	v_pk_mul_f32 v[30:31], v[26:27], v[66:67] op_sel_hi:[1,0]
	v_pk_mul_f32 v[32:33], v[22:23], v[66:67] op_sel_hi:[1,0]
	v_pk_mul_f32 v[28:29], v[24:25], v[66:67] op_sel_hi:[1,0]
	v_pk_mul_f32 v[22:23], v[14:15], v[60:61]
	v_pk_mul_f32 v[24:25], v[16:17], v[62:63]
	v_mul_f32_e64 v60, v67, -v66
	v_pk_mul_f32 v[26:27], v[64:65], v[66:67] op_sel_hi:[1,0]
	v_pk_fma_f32 v[24:25], v[60:61], v[32:33], v[24:25] op_sel_hi:[0,1,1]
	v_pk_fma_f32 v[22:23], v[60:61], v[30:31], v[22:23] op_sel_hi:[0,1,1]
	v_and_b32_e32 v62, 0xffff0000, v55
	v_lshlrev_b32_e32 v60, 16, v55
	v_and_b32_e32 v66, 0xffff0000, v54
	v_lshlrev_b32_e32 v64, 16, v54
	ds_write_b128 v133, v[14:17] offset:24576
	s_mov_b32 exec_lo, 0xffff0000
	ds_read_b128 v[140:143], v133 offset:24320
	s_mov_b32 exec_lo, 0
	ds_read_b128 v[144:147], v133 offset:24064
	s_mov_b32 exec_hi, 0xffff0000
	ds_read_b128 v[148:151], v133 offset:23808
	s_mov_b64 exec, -1
	v_mov_b32_e32 v152, 1.0
	v_mov_b32_e32 v153, 1.0
	v_mov_b32_e32 v154, 1.0
	v_mov_b32_e32 v155, 1.0
	s_waitcnt lgkmcnt(0)
	s_mov_b32 exec_lo, 0xffff0000
	v_pk_mul_f32 v[152:153], v[152:153], v[140:141]
	v_pk_mul_f32 v[154:155], v[154:155], v[142:143]
	s_mov_b32 exec_lo, 0
	v_pk_mul_f32 v[152:153], v[152:153], v[144:145]
	v_pk_mul_f32 v[154:155], v[154:155], v[146:147]
	s_mov_b32 exec_hi, 0xffff0000
	v_pk_mul_f32 v[152:153], v[152:153], v[148:149]
	v_pk_mul_f32 v[154:155], v[154:155], v[150:151]
	s_mov_b64 exec, -1
	v_pk_mul_f32 v[156:157], v[152:153], v[14:15]
	v_pk_mul_f32 v[158:159], v[154:155], v[16:17]
	v_rcp_f32_e32 v160, v156
	v_rcp_f32_e32 v161, v157
	v_rcp_f32_e32 v162, v158
	v_rcp_f32_e32 v163, v159
	s_mov_b32 exec_lo, 0
	s_mov_b32 exec_hi, 0xffff0000
	v_mov_b32_e32 v160, 1.0
	v_mov_b32_e32 v161, 1.0
	v_mov_b32_e32 v162, 1.0
	v_mov_b32_e32 v163, 1.0
	ds_write_b128 v133, v[156:159] offset:24576
	s_mov_b64 exec, -1
	v_pk_mul_f32 v[164:165], v[18:19], v[160:161]
	v_pk_mul_f32 v[166:167], v[20:21], v[162:163]
	ds_write_b128 v133, v[164:167] offset:16384
	v_pk_mul_f32 v[168:169], v[26:27], v[160:161]
	v_pk_mul_f32 v[170:171], v[28:29], v[162:163]
	ds_write_b128 v133, v[168:171] offset:32768
	v_pk_mul_f32 v[172:173], v[30:31], v[152:153]
	v_pk_mul_f32 v[174:175], v[32:33], v[154:155]
	v_pk_mul_f32 v[176:177], v[22:23], v[152:153]
	v_pk_mul_f32 v[178:179], v[24:25], v[154:155]
	v_add_u32_e32 v201, 0x2000, v133
	ds_write2_b32 v133, v172, v176 offset1:1
	ds_write2_b32 v133, v173, v177 offset0:2 offset1:3
	ds_write2_b32 v201, v174, v178 offset1:1
	ds_write2_b32 v201, v175, v179 offset0:2 offset1:3
	v_mul_f32_e32 v65, v59, v64
	v_mul_f32_e32 v67, v59, v66
	v_add_u32_e32 v14, v132, v127
	v_mul_f32_e32 v61, v59, v60
	v_mul_f32_e32 v63, v59, v62
	v_readlane_b32 s98, v255, 2
	s_nop 3
	s_mov_b32 exec_lo, s98
	s_mov_b32 exec_hi, s98
	ds_write_b128 v14, v[64:67]
	ds_write_b128 v14, v[60:63] offset:16
	s_mov_b64 exec, -1
	v_lshlrev_b64 v[14:15], 6, v[46:47]
	v_lshl_add_u64 v[14:15], s[12:13], 0, v[14:15]
	s_and_saveexec_b64 s[12:13], s[0:1]
	s_cbranch_execz .LBB0_192
	global_store_dword v[14:15], v58, off
.LBB0_192:
	s_or_b64 exec, exec, s[12:13]
	s_waitcnt vmcnt(1)
	v_lshlrev_b32_e32 v16, 16, v56
	s_waitcnt vmcnt(0)
	v_lshlrev_b32_e32 v20, 16, v52
	v_and_b32_e32 v21, 0xffff0000, v52
	v_exp_f32_e32 v18, v16
	v_lshlrev_b32_e32 v16, 16, v48
	v_and_b32_e32 v17, 0xffff0000, v48
	v_pk_fma_f32 v[22:23], v[20:21], v[2:3], v[38:39]
	v_lshlrev_b32_e32 v46, 16, v50
	v_and_b32_e32 v47, 0xffff0000, v50
	v_pk_mul_f32 v[22:23], v[22:23], v[16:17]
	v_pk_mul_f32 v[26:27], v[6:7], v[16:17]
	v_pk_mul_f32 v[16:17], v[22:23], v[46:47]
	v_lshlrev_b32_e32 v30, 16, v53
	v_and_b32_e32 v31, 0xffff0000, v53
	v_fma_f32 v16, v16, v10, 0
	v_lshlrev_b32_e32 v24, 16, v49
	v_and_b32_e32 v25, 0xffff0000, v49
	v_pk_fma_f32 v[32:33], v[30:31], v[4:5], v[40:41]
	v_pk_mul_f32 v[48:49], v[26:27], v[20:21]
	v_and_b32_e32 v19, 0xffff0000, v56
	v_fma_f32 v56, v26, v26, 0
	v_fma_f32 v58, v22, v46, 0
	v_fmac_f32_e32 v16, v17, v11
	v_lshlrev_b32_e32 v50, 16, v51
	v_and_b32_e32 v51, 0xffff0000, v51
	v_pk_mul_f32 v[28:29], v[8:9], v[24:25]
	v_pk_mul_f32 v[24:25], v[32:33], v[24:25]
	v_fma_f32 v17, v48, v46, 0
	v_fmac_f32_e32 v56, v27, v27
	v_fmac_f32_e32 v58, v23, v47
	v_pk_mul_f32 v[32:33], v[24:25], v[50:51]
	v_fmac_f32_e32 v17, v49, v47
	v_pk_mul_f32 v[30:31], v[28:29], v[30:31]
	v_fmac_f32_e32 v56, v28, v28
	v_fmac_f32_e32 v16, v32, v12
	v_fmac_f32_e32 v58, v24, v50
	v_fmac_f32_e32 v17, v30, v50
	v_fmac_f32_e32 v56, v29, v29
	v_fmac_f32_e32 v16, v33, v13
	v_fmac_f32_e32 v58, v25, v51
	v_fmac_f32_e32 v17, v31, v51
	s_nop 1
	v_add_f32_dpp v56, v56, v56 quad_perm:[1,0,3,2] row_mask:0xf bank_mask:0xf
	v_add_f32_dpp v16, v16, v16 quad_perm:[1,0,3,2] row_mask:0xf bank_mask:0xf
	v_add_f32_dpp v17, v17, v17 quad_perm:[1,0,3,2] row_mask:0xf bank_mask:0xf
	v_add_f32_dpp v58, v58, v58 quad_perm:[1,0,3,2] row_mask:0xf bank_mask:0xf
	v_add_f32_dpp v56, v56, v56 quad_perm:[2,3,0,1] row_mask:0xf bank_mask:0xf
	v_add_f32_dpp v16, v16, v16 quad_perm:[2,3,0,1] row_mask:0xf bank_mask:0xf
	v_add_f32_dpp v17, v17, v17 quad_perm:[2,3,0,1] row_mask:0xf bank_mask:0xf
	v_add_f32_dpp v58, v58, v58 quad_perm:[2,3,0,1] row_mask:0xf bank_mask:0xf
	v_add_f32_dpp v56, v56, v56 row_half_mirror row_mask:0xf bank_mask:0xf
	v_add_f32_dpp v16, v16, v16 row_half_mirror row_mask:0xf bank_mask:0xf
	v_add_f32_dpp v17, v17, v17 row_half_mirror row_mask:0xf bank_mask:0xf
	v_add_f32_dpp v58, v58, v58 row_half_mirror row_mask:0xf bank_mask:0xf
	v_add_f32_dpp v56, v56, v56 row_mirror row_mask:0xf bank_mask:0xf
	v_add_f32_dpp v16, v16, v16 row_mirror row_mask:0xf bank_mask:0xf
	v_add_f32_dpp v17, v17, v17 row_mirror row_mask:0xf bank_mask:0xf
	v_add_f32_dpp v58, v58, v58 row_mirror row_mask:0xf bank_mask:0xf
	s_nop 0
	v_lshlrev_b32_e32 v54, 16, v57
	v_max_f32_e32 v20, v56, v56
	v_and_b32_e32 v55, 0xffff0000, v57
	v_max_f32_e32 v20, 0x179abe15, v20
	v_rsq_f32_e32 v52, v20
	v_exp_f32_e32 v19, v19
	v_exp_f32_e32 v20, v54
	v_exp_f32_e32 v21, v55
	v_pk_mul_f32 v[26:27], v[26:27], v[52:53] op_sel_hi:[1,0]
	v_pk_mul_f32 v[28:29], v[28:29], v[52:53] op_sel_hi:[1,0]
	v_pk_mul_f32 v[32:33], v[30:31], v[52:53] op_sel_hi:[1,0]
	v_pk_mul_f32 v[30:31], v[48:49], v[52:53] op_sel_hi:[1,0]
	v_pk_mul_f32 v[46:47], v[18:19], v[46:47]
	v_pk_mul_f32 v[48:49], v[20:21], v[50:51]
	v_mul_f32_e64 v50, v17, -v52
	v_pk_fma_f32 v[48:49], v[50:51], v[28:29], v[48:49] op_sel_hi:[0,1,1]
	v_pk_fma_f32 v[46:47], v[50:51], v[26:27], v[46:47] op_sel_hi:[0,1,1]
	v_and_b32_e32 v52, 0xffff0000, v45
	v_lshlrev_b32_e32 v50, 16, v45
	v_and_b32_e32 v56, 0xffff0000, v44
	v_lshlrev_b32_e32 v54, 16, v44
	v_mul_f32_e32 v55, v58, v54
	v_mul_f32_e32 v57, v58, v56
	v_add_u32_e32 v17, v132, v130
	v_mul_f32_e32 v51, v58, v50
	v_mul_f32_e32 v53, v58, v52
	ds_write_b128 v134, v[18:21] offset:24576
	s_mov_b32 exec_lo, 0xffff0000
	ds_read_b128 v[140:143], v134 offset:24320
	s_mov_b32 exec_lo, 0
	ds_read_b128 v[144:147], v134 offset:24064
	s_mov_b32 exec_hi, 0xffff0000
	ds_read_b128 v[148:151], v134 offset:23808
	s_mov_b64 exec, -1
	v_mov_b32_e32 v152, 1.0
	v_mov_b32_e32 v153, 1.0
	v_mov_b32_e32 v154, 1.0
	v_mov_b32_e32 v155, 1.0
	s_waitcnt lgkmcnt(0)
	s_mov_b32 exec_lo, 0xffff0000
	v_pk_mul_f32 v[152:153], v[152:153], v[140:141]
	v_pk_mul_f32 v[154:155], v[154:155], v[142:143]
	s_mov_b32 exec_lo, 0
	v_pk_mul_f32 v[152:153], v[152:153], v[144:145]
	v_pk_mul_f32 v[154:155], v[154:155], v[146:147]
	s_mov_b32 exec_hi, 0xffff0000
	v_pk_mul_f32 v[152:153], v[152:153], v[148:149]
	v_pk_mul_f32 v[154:155], v[154:155], v[150:151]
	s_mov_b64 exec, -1
	v_pk_mul_f32 v[156:157], v[152:153], v[18:19]
	v_pk_mul_f32 v[158:159], v[154:155], v[20:21]
	v_rcp_f32_e32 v160, v156
	v_rcp_f32_e32 v161, v157
	v_rcp_f32_e32 v162, v158
	v_rcp_f32_e32 v163, v159
	s_mov_b32 exec_lo, 0
	s_mov_b32 exec_hi, 0xffff0000
	v_mov_b32_e32 v160, 1.0
	v_mov_b32_e32 v161, 1.0
	v_mov_b32_e32 v162, 1.0
	v_mov_b32_e32 v163, 1.0
	ds_write_b128 v134, v[156:159] offset:24576
	s_mov_b64 exec, -1
	v_pk_mul_f32 v[164:165], v[22:23], v[160:161]
	v_pk_mul_f32 v[166:167], v[24:25], v[162:163]
	ds_write_b128 v134, v[164:167] offset:16384
	v_pk_mul_f32 v[168:169], v[30:31], v[160:161]
	v_pk_mul_f32 v[170:171], v[32:33], v[162:163]
	ds_write_b128 v134, v[168:171] offset:32768
	v_pk_mul_f32 v[172:173], v[26:27], v[152:153]
	v_pk_mul_f32 v[174:175], v[28:29], v[154:155]
	v_pk_mul_f32 v[176:177], v[46:47], v[152:153]
	v_pk_mul_f32 v[178:179], v[48:49], v[154:155]
	v_add_u32_e32 v201, 0x2000, v134
	ds_write2_b32 v134, v172, v176 offset1:1
	ds_write2_b32 v134, v173, v177 offset0:2 offset1:3
	ds_write2_b32 v201, v174, v178 offset1:1
	ds_write2_b32 v201, v175, v179 offset0:2 offset1:3
	v_readlane_b32 s98, v255, 2
	s_nop 3
	s_mov_b32 exec_lo, s98
	s_mov_b32 exec_hi, s98
	ds_write_b128 v17, v[54:57]
	ds_write_b128 v17, v[50:53] offset:16
	s_mov_b64 exec, -1
	s_and_saveexec_b64 s[12:13], s[0:1]
	s_cbranch_execz .LBB0_194
	global_store_dword v[14:15], v16, off offset:1024

.LBB0_197:
	s_andn2_b32 s2, 0x400, s13
	v_lshl_add_u32 v48, s2, 2, v131
	v_readlane_b32 s20, v248, 7
	ds_read_b128 v[48:51], v48
	v_readlane_b32 s21, v248, 8
	s_waitcnt lgkmcnt(0)
	v_cvt_pk_bf16_f32 v48, v48, v49
	v_cvt_pk_bf16_f32 v49, v50, v51
	s_cmp_eq_u32 s12, 64
	v_readlane_b32 s22, v248, 9
	v_lshl_add_u64 v[50:51], s[20:21], 0, v[18:19]
	v_readlane_b32 s23, v248, 10
	global_store_dwordx2 v[50:51], v[48:49], off
	s_cbranch_scc1 .LBB0_196
	s_waitcnt vmcnt(7)
	v_lshlrev_b32_e32 v60, 16, v44
	v_and_b32_e32 v61, 0xffff0000, v44
	v_lshlrev_b32_e32 v52, 16, v32
	v_and_b32_e32 v53, 0xffff0000, v32
	v_pk_fma_f32 v[54:55], v[60:61], v[2:3], v[38:39]
	v_lshlrev_b32_e32 v50, 16, v46
	v_and_b32_e32 v51, 0xffff0000, v46
	v_lshlrev_b32_e32 v69, 16, v47
	v_and_b32_e32 v70, 0xffff0000, v47
	v_lshlrev_b32_e32 v46, 16, v42
	v_and_b32_e32 v47, 0xffff0000, v42
	v_pk_mul_f32 v[54:55], v[54:55], v[52:53]
	v_pk_mul_f32 v[58:59], v[6:7], v[52:53]
	v_pk_mul_f32 v[52:53], v[54:55], v[46:47]
	v_lshlrev_b32_e32 v44, 16, v45
	v_fma_f32 v32, v52, v10, 0
	v_and_b32_e32 v45, 0xffff0000, v45
	v_fmac_f32_e32 v32, v53, v11
	v_lshlrev_b32_e32 v62, 16, v43
	v_and_b32_e32 v63, 0xffff0000, v43
	v_lshlrev_b32_e32 v42, 16, v33
	v_and_b32_e32 v43, 0xffff0000, v33
	v_pk_fma_f32 v[52:53], v[44:45], v[4:5], v[40:41]
	v_pk_mul_f32 v[66:67], v[58:59], v[60:61]
	v_fma_f32 v68, v58, v58, 0
	v_fma_f32 v74, v54, v46, 0
	v_pk_mul_f32 v[64:65], v[8:9], v[42:43]
	v_pk_mul_f32 v[56:57], v[52:53], v[42:43]
	v_fma_f32 v33, v66, v46, 0
	v_fmac_f32_e32 v68, v59, v59
	v_fmac_f32_e32 v74, v55, v47
	v_pk_mul_f32 v[42:43], v[56:57], v[62:63]
	v_fmac_f32_e32 v33, v67, v47
	v_pk_mul_f32 v[60:61], v[64:65], v[44:45]
	v_fmac_f32_e32 v68, v64, v64
	v_fmac_f32_e32 v32, v42, v12
	v_fmac_f32_e32 v74, v56, v62
	v_fmac_f32_e32 v33, v60, v62
	v_fmac_f32_e32 v68, v65, v65
	v_fmac_f32_e32 v32, v43, v13
	v_fmac_f32_e32 v74, v57, v63
	v_fmac_f32_e32 v33, v61, v63
	s_nop 1
	v_add_f32_dpp v68, v68, v68 quad_perm:[1,0,3,2] row_mask:0xf bank_mask:0xf
	v_add_f32_dpp v32, v32, v32 quad_perm:[1,0,3,2] row_mask:0xf bank_mask:0xf
	v_add_f32_dpp v33, v33, v33 quad_perm:[1,0,3,2] row_mask:0xf bank_mask:0xf
	v_add_f32_dpp v74, v74, v74 quad_perm:[1,0,3,2] row_mask:0xf bank_mask:0xf
	v_add_f32_dpp v68, v68, v68 quad_perm:[2,3,0,1] row_mask:0xf bank_mask:0xf
	v_add_f32_dpp v32, v32, v32 quad_perm:[2,3,0,1] row_mask:0xf bank_mask:0xf
	v_add_f32_dpp v33, v33, v33 quad_perm:[2,3,0,1] row_mask:0xf bank_mask:0xf
	v_add_f32_dpp v74, v74, v74 quad_perm:[2,3,0,1] row_mask:0xf bank_mask:0xf
	v_add_f32_dpp v68, v68, v68 row_half_mirror row_mask:0xf bank_mask:0xf
	v_add_f32_dpp v32, v32, v32 row_half_mirror row_mask:0xf bank_mask:0xf
	v_add_f32_dpp v33, v33, v33 row_half_mirror row_mask:0xf bank_mask:0xf
	v_add_f32_dpp v74, v74, v74 row_half_mirror row_mask:0xf bank_mask:0xf
	v_add_f32_dpp v68, v68, v68 row_mirror row_mask:0xf bank_mask:0xf
	v_add_f32_dpp v32, v32, v32 row_mirror row_mask:0xf bank_mask:0xf
	v_add_f32_dpp v33, v33, v33 row_mirror row_mask:0xf bank_mask:0xf
	v_add_f32_dpp v74, v74, v74 row_mirror row_mask:0xf bank_mask:0xf
	s_nop 0
	v_exp_f32_e32 v50, v50
	v_max_f32_e32 v42, v68, v68
	v_max_f32_e32 v42, 0x179abe15, v42
	v_rsq_f32_e32 v68, v42
	v_exp_f32_e32 v51, v51
	v_exp_f32_e32 v52, v69
	v_exp_f32_e32 v53, v70
	s_bitcmp1_b32 s12, 0
	s_cselect_b32 s2, 0xe000, 0
	v_readlane_b32 s3, v251, 27
	s_add_i32 s2, s3, s2
	v_add_u32_e32 v49, s2, v122
	v_pk_mul_f32 v[42:43], v[58:59], v[68:69] op_sel_hi:[1,0]
	v_pk_mul_f32 v[44:45], v[64:65], v[68:69] op_sel_hi:[1,0]
	v_pk_mul_f32 v[58:59], v[66:67], v[68:69] op_sel_hi:[1,0]
	v_pk_mul_f32 v[46:47], v[50:51], v[46:47]
	v_pk_mul_f32 v[62:63], v[52:53], v[62:63]
	v_mul_f32_e64 v66, v33, -v68
	v_add_u32_e32 v48, s2, v123
	v_pk_mul_f32 v[60:61], v[60:61], v[68:69] op_sel_hi:[1,0]
	v_pk_fma_f32 v[64:65], v[66:67], v[44:45], v[62:63] op_sel_hi:[0,1,1]
	v_pk_fma_f32 v[62:63], v[66:67], v[42:43], v[46:47] op_sel_hi:[0,1,1]
	s_waitcnt vmcnt(4)
	v_and_b32_e32 v68, 0xffff0000, v31
	v_lshlrev_b32_e32 v66, 16, v31
	v_and_b32_e32 v72, 0xffff0000, v30
	v_lshlrev_b32_e32 v70, 16, v30
	v_add_u32_e32 v30, v49, v125
	ds_write_b128 v30, v[50:53] offset:24576
	s_mov_b32 exec_lo, 0xffff0000
	ds_read_b128 v[140:143], v30 offset:24320
	s_mov_b32 exec_lo, 0
	ds_read_b128 v[144:147], v30 offset:24064
	s_mov_b32 exec_hi, 0xffff0000
	ds_read_b128 v[148:151], v30 offset:23808
	s_mov_b64 exec, -1
	v_mov_b32_e32 v152, 1.0
	v_mov_b32_e32 v153, 1.0
	v_mov_b32_e32 v154, 1.0
	v_mov_b32_e32 v155, 1.0
	s_waitcnt lgkmcnt(0)
	s_mov_b32 exec_lo, 0xffff0000
	v_pk_mul_f32 v[152:153], v[152:153], v[140:141]
	v_pk_mul_f32 v[154:155], v[154:155], v[142:143]
	s_mov_b32 exec_lo, 0
	v_pk_mul_f32 v[152:153], v[152:153], v[144:145]
	v_pk_mul_f32 v[154:155], v[154:155], v[146:147]
	s_mov_b32 exec_hi, 0xffff0000
	v_pk_mul_f32 v[152:153], v[152:153], v[148:149]
	v_pk_mul_f32 v[154:155], v[154:155], v[150:151]
	s_mov_b64 exec, -1
	v_pk_mul_f32 v[156:157], v[152:153], v[50:51]
	v_pk_mul_f32 v[158:159], v[154:155], v[52:53]
	v_rcp_f32_e32 v160, v156
	v_rcp_f32_e32 v161, v157
	v_rcp_f32_e32 v162, v158
	v_rcp_f32_e32 v163, v159
	s_mov_b32 exec_lo, 0
	s_mov_b32 exec_hi, 0xffff0000
	v_mov_b32_e32 v160, 1.0
	v_mov_b32_e32 v161, 1.0
	v_mov_b32_e32 v162, 1.0
	v_mov_b32_e32 v163, 1.0
	ds_write_b128 v30, v[156:159] offset:24576
	s_mov_b64 exec, -1
	v_pk_mul_f32 v[164:165], v[54:55], v[160:161]
	v_pk_mul_f32 v[166:167], v[56:57], v[162:163]
	ds_write_b128 v30, v[164:167] offset:16384
	v_pk_mul_f32 v[168:169], v[58:59], v[160:161]
	v_pk_mul_f32 v[170:171], v[60:61], v[162:163]
	ds_write_b128 v30, v[168:171] offset:32768
	v_pk_mul_f32 v[172:173], v[42:43], v[152:153]
	v_pk_mul_f32 v[174:175], v[44:45], v[154:155]
	v_pk_mul_f32 v[176:177], v[62:63], v[152:153]
	v_pk_mul_f32 v[178:179], v[64:65], v[154:155]
	v_add_u32_e32 v201, 0x2000, v30
	ds_write2_b32 v30, v172, v176 offset1:1
	ds_write2_b32 v30, v173, v177 offset0:2 offset1:3
	ds_write2_b32 v201, v174, v178 offset1:1
	ds_write2_b32 v201, v175, v179 offset0:2 offset1:3
	v_add_u32_e32 v30, v48, v127
	v_mul_f32_e32 v71, v74, v70
	v_mul_f32_e32 v73, v74, v72
	v_mul_f32_e32 v67, v74, v66
	v_mul_f32_e32 v69, v74, v68
	v_readlane_b32 s98, v255, 2
	s_nop 3
	s_mov_b32 exec_lo, s98
	s_mov_b32 exec_hi, s98
	ds_write_b128 v30, v[70:73] offset:40960
	ds_write_b128 v30, v[66:69] offset:40976
	s_mov_b64 exec, -1
	v_lshl_add_u64 v[30:31], s[20:21], 0, v[16:17]
	s_and_saveexec_b64 s[2:3], s[0:1]
	s_cbranch_execz .LBB0_200
	v_add_co_u32_e32 v42, vcc, 0x15d01000, v30
	s_nop 1
	v_addc_co_u32_e32 v43, vcc, 0, v31, vcc
	global_store_dword v[42:43], v32, off
.LBB0_200:
	s_or_b64 exec, exec, s[2:3]
	s_waitcnt vmcnt(2)
	v_lshlrev_b32_e32 v32, 16, v28
	s_waitcnt vmcnt(1)
	v_lshlrev_b32_e32 v44, 16, v26
	v_and_b32_e32 v45, 0xffff0000, v26
	v_exp_f32_e32 v42, v32
	v_lshlrev_b32_e32 v32, 16, v24
	v_and_b32_e32 v33, 0xffff0000, v24
	v_pk_fma_f32 v[50:51], v[44:45], v[2:3], v[38:39]
	v_and_b32_e32 v43, 0xffff0000, v28
	v_lshlrev_b32_e32 v61, 16, v29
	v_and_b32_e32 v62, 0xffff0000, v29
	v_lshlrev_b32_e32 v28, 16, v22
	v_and_b32_e32 v29, 0xffff0000, v22
	v_pk_mul_f32 v[50:51], v[50:51], v[32:33]
	v_pk_mul_f32 v[46:47], v[6:7], v[32:33]
	v_pk_mul_f32 v[32:33], v[50:51], v[28:29]
	v_lshlrev_b32_e32 v26, 16, v27
	v_and_b32_e32 v27, 0xffff0000, v27
	v_fma_f32 v22, v32, v10, 0
	v_lshlrev_b32_e32 v24, 16, v25
	v_and_b32_e32 v25, 0xffff0000, v25
	v_pk_fma_f32 v[52:53], v[26:27], v[4:5], v[40:41]
	v_pk_mul_f32 v[58:59], v[46:47], v[44:45]
	v_fma_f32 v60, v46, v46, 0
	v_fma_f32 v65, v50, v28, 0
	v_fmac_f32_e32 v22, v33, v11
	v_lshlrev_b32_e32 v32, 16, v23
	v_and_b32_e32 v33, 0xffff0000, v23
	v_pk_mul_f32 v[54:55], v[8:9], v[24:25]
	v_pk_mul_f32 v[52:53], v[52:53], v[24:25]
	v_fma_f32 v23, v58, v28, 0
	v_fmac_f32_e32 v60, v47, v47
	v_fmac_f32_e32 v65, v51, v29
	v_pk_mul_f32 v[24:25], v[52:53], v[32:33]
	v_fmac_f32_e32 v23, v59, v29
	v_pk_mul_f32 v[56:57], v[54:55], v[26:27]
	v_fmac_f32_e32 v60, v54, v54
	v_fmac_f32_e32 v22, v24, v12
	v_fmac_f32_e32 v65, v52, v32
	v_fmac_f32_e32 v23, v56, v32
	v_fmac_f32_e32 v60, v55, v55
	v_fmac_f32_e32 v22, v25, v13
	v_fmac_f32_e32 v65, v53, v33
	v_fmac_f32_e32 v23, v57, v33
	s_nop 1
	v_add_f32_dpp v60, v60, v60 quad_perm:[1,0,3,2] row_mask:0xf bank_mask:0xf
	v_add_f32_dpp v22, v22, v22 quad_perm:[1,0,3,2] row_mask:0xf bank_mask:0xf
	v_add_f32_dpp v23, v23, v23 quad_perm:[1,0,3,2] row_mask:0xf bank_mask:0xf
	v_add_f32_dpp v65, v65, v65 quad_perm:[1,0,3,2] row_mask:0xf bank_mask:0xf
	v_add_f32_dpp v60, v60, v60 quad_perm:[2,3,0,1] row_mask:0xf bank_mask:0xf
	v_add_f32_dpp v22, v22, v22 quad_perm:[2,3,0,1] row_mask:0xf bank_mask:0xf
	v_add_f32_dpp v23, v23, v23 quad_perm:[2,3,0,1] row_mask:0xf bank_mask:0xf
	v_add_f32_dpp v65, v65, v65 quad_perm:[2,3,0,1] row_mask:0xf bank_mask:0xf
	v_add_f32_dpp v60, v60, v60 row_half_mirror row_mask:0xf bank_mask:0xf
	v_add_f32_dpp v22, v22, v22 row_half_mirror row_mask:0xf bank_mask:0xf
	v_add_f32_dpp v23, v23, v23 row_half_mirror row_mask:0xf bank_mask:0xf
	v_add_f32_dpp v65, v65, v65 row_half_mirror row_mask:0xf bank_mask:0xf
	v_add_f32_dpp v60, v60, v60 row_mirror row_mask:0xf bank_mask:0xf
	v_add_f32_dpp v22, v22, v22 row_mirror row_mask:0xf bank_mask:0xf
	v_add_f32_dpp v23, v23, v23 row_mirror row_mask:0xf bank_mask:0xf
	v_add_f32_dpp v65, v65, v65 row_mirror row_mask:0xf bank_mask:0xf
	s_nop 0
	v_exp_f32_e32 v43, v43
	v_max_f32_e32 v24, v60, v60
	v_max_f32_e32 v24, 0x179abe15, v24
	v_rsq_f32_e32 v60, v24
	v_exp_f32_e32 v44, v61
	v_exp_f32_e32 v45, v62
	v_pk_mul_f32 v[28:29], v[42:43], v[28:29]
	v_pk_mul_f32 v[24:25], v[46:47], v[60:61] op_sel_hi:[1,0]
	v_pk_mul_f32 v[26:27], v[54:55], v[60:61] op_sel_hi:[1,0]
	v_pk_mul_f32 v[32:33], v[44:45], v[32:33]
	v_mul_f32_e64 v46, v23, -v60
	v_and_b32_e32 v64, 0xffff0000, v21
	v_lshlrev_b32_e32 v62, 16, v21
	v_and_b32_e32 v68, 0xffff0000, v20
	v_lshlrev_b32_e32 v66, 16, v20
	v_add_u32_e32 v20, v49, v128
	v_pk_mul_f32 v[56:57], v[56:57], v[60:61] op_sel_hi:[1,0]
	v_pk_mul_f32 v[54:55], v[58:59], v[60:61] op_sel_hi:[1,0]
	v_pk_fma_f32 v[60:61], v[46:47], v[26:27], v[32:33] op_sel_hi:[0,1,1]
	v_pk_fma_f32 v[58:59], v[46:47], v[24:25], v[28:29] op_sel_hi:[0,1,1]
	ds_write_b128 v20, v[42:45] offset:24576
	s_mov_b32 exec_lo, 0xffff0000
	ds_read_b128 v[140:143], v20 offset:24320
	s_mov_b32 exec_lo, 0
	ds_read_b128 v[144:147], v20 offset:24064
	s_mov_b32 exec_hi, 0xffff0000
	ds_read_b128 v[148:151], v20 offset:23808
	s_mov_b64 exec, -1
	v_mov_b32_e32 v152, 1.0
	v_mov_b32_e32 v153, 1.0
	v_mov_b32_e32 v154, 1.0
	v_mov_b32_e32 v155, 1.0
	s_waitcnt lgkmcnt(0)
	s_mov_b32 exec_lo, 0xffff0000
	v_pk_mul_f32 v[152:153], v[152:153], v[140:141]
	v_pk_mul_f32 v[154:155], v[154:155], v[142:143]
	s_mov_b32 exec_lo, 0
	v_pk_mul_f32 v[152:153], v[152:153], v[144:145]
	v_pk_mul_f32 v[154:155], v[154:155], v[146:147]
	s_mov_b32 exec_hi, 0xffff0000
	v_pk_mul_f32 v[152:153], v[152:153], v[148:149]
	v_pk_mul_f32 v[154:155], v[154:155], v[150:151]
	s_mov_b64 exec, -1
	v_pk_mul_f32 v[156:157], v[152:153], v[42:43]
	v_pk_mul_f32 v[158:159], v[154:155], v[44:45]
	v_rcp_f32_e32 v160, v156
	v_rcp_f32_e32 v161, v157
	v_rcp_f32_e32 v162, v158
	v_rcp_f32_e32 v163, v159
	s_mov_b32 exec_lo, 0
	s_mov_b32 exec_hi, 0xffff0000
	v_mov_b32_e32 v160, 1.0
	v_mov_b32_e32 v161, 1.0
	v_mov_b32_e32 v162, 1.0
	v_mov_b32_e32 v163, 1.0
	ds_write_b128 v20, v[156:159] offset:24576
	s_mov_b64 exec, -1
	v_pk_mul_f32 v[164:165], v[50:51], v[160:161]
	v_pk_mul_f32 v[166:167], v[52:53], v[162:163]
	ds_write_b128 v20, v[164:167] offset:16384
	v_pk_mul_f32 v[168:169], v[54:55], v[160:161]
	v_pk_mul_f32 v[170:171], v[56:57], v[162:163]
	ds_write_b128 v20, v[168:171] offset:32768
	v_pk_mul_f32 v[172:173], v[24:25], v[152:153]
	v_pk_mul_f32 v[174:175], v[26:27], v[154:155]
	v_pk_mul_f32 v[176:177], v[58:59], v[152:153]
	v_pk_mul_f32 v[178:179], v[60:61], v[154:155]
	v_add_u32_e32 v201, 0x2000, v20
	ds_write2_b32 v20, v172, v176 offset1:1
	ds_write2_b32 v20, v173, v177 offset0:2 offset1:3
	ds_write2_b32 v201, v174, v178 offset1:1
	ds_write2_b32 v201, v175, v179 offset0:2 offset1:3
	v_add_u32_e32 v20, v48, v130
	v_mul_f32_e32 v67, v65, v66
	v_mul_f32_e32 v69, v65, v68
	v_mul_f32_e32 v63, v65, v62
	v_mul_f32_e32 v65, v65, v64
	v_readlane_b32 s98, v255, 2
	s_nop 3
	s_mov_b32 exec_lo, s98
	s_mov_b32 exec_hi, s98
	ds_write_b128 v20, v[66:69] offset:40960
	ds_write_b128 v20, v[62:65] offset:40976
	s_mov_b64 exec, -1
	s_and_saveexec_b64 s[2:3], s[0:1]
	s_cbranch_execz .LBB0_195
	v_add_co_u32_e32 v20, vcc, 0x15d01000, v30
	s_nop 1
	v_addc_co_u32_e32 v21, vcc, 0, v31, vcc
	global_store_dword v[20:21], v22, off offset:1024
	s_branch .LBB0_195
